# grid barrier: non-last XCD leaders poll the arrival counter directly; last leader skips the generation-word atomic
# speedup vs baseline: 1.0034x; 1.0034x over previous
.LBB0_155:
	s_andn2_saveexec_b64 s[2:3], s[2:3]
	s_cbranch_execz .LBB0_171
	v_mov_b32_e32 v2, s36
	v_add_co_u32_e32 v2, vcc, 0x8d43000, v2
	v_mov_b32_e32 v3, s37
	buffer_wbl2 sc1
	s_waitcnt vmcnt(0)
	v_addc_co_u32_e32 v3, vcc, 0, v3, vcc
	global_atomic_add v2, v[2:3], v218, off offset:1024 sc0
	v_cvt_f32_u32_e32 v3, v0
	v_sub_u32_e32 v5, 0, v0
	s_add_u32 s2, s36, 0x8d43500
	s_addc_u32 s3, s37, 0
	v_rcp_iflag_f32_e32 v3, v3
	s_mov_b64 s[6:7], -1
	v_mul_f32_e32 v3, 0x4f7ffffe, v3
	v_cvt_u32_f32_e32 v3, v3
	v_mul_lo_u32 v5, v5, v3
	v_mul_hi_u32 v5, v3, v5
	v_add_u32_e32 v3, v3, v5
	s_waitcnt vmcnt(0) lgkmcnt(0)
	v_mul_hi_u32 v3, v2, v3
	v_mul_lo_u32 v5, v3, v0
	v_add_u32_e32 v6, 1, v2
	v_sub_u32_e32 v2, v2, v5
	v_add_u32_e32 v7, 1, v3
	v_cmp_ge_u32_e32 vcc, v2, v0
	v_sub_u32_e32 v5, v2, v0
	s_nop 0
	v_cndmask_b32_e32 v3, v3, v7, vcc
	v_cndmask_b32_e32 v2, v2, v5, vcc
	v_add_u32_e32 v5, 1, v3
	v_cmp_ge_u32_e32 vcc, v2, v0
	s_nop 1
	v_cndmask_b32_e32 v5, v3, v5, vcc
	v_mad_u64_u32 v[2:3], s[4:5], v0, v5, v[0:1]
	v_cmp_ne_u32_e32 vcc, v6, v2
	v_mov_b32_e32 v7, v2
	v_mov_b64_e32 v[2:3], s[2:3]
	s_and_saveexec_b64 s[4:5], vcc
	s_cbranch_execz .LBB0_168
	v_mov_b64_e32 v[2:3], s[2:3]
	global_load_dword v0, v[2:3], off offset:-256 sc1
	s_mov_b64 s[10:11], 0
	s_waitcnt vmcnt(0) lgkmcnt(0)
	v_cmp_lt_u32_e32 vcc, v0, v7
	s_and_saveexec_b64 s[8:9], vcc
	s_cbranch_execz .LBB0_167
	s_add_u32 s6, s36, 0x8d40200
	s_addc_u32 s7, s37, 0
	s_mov_b32 s22, 1
	s_branch .LBB0_160

.LBB0_165:
	v_mov_b64_e32 v[2:3], s[2:3]
	global_load_dword v0, v[2:3], off offset:-256 sc1
	s_add_i32 s22, s22, 1
	s_or_b64 s[16:17], s[16:17], exec
	s_waitcnt vmcnt(0) lgkmcnt(0)
	v_cmp_ge_u32_e32 vcc, v0, v7
	s_orn2_b64 s[14:15], vcc, exec
	s_branch .LBB0_159

.LBB0_168:
	s_or_b64 exec, exec, s[4:5]
	s_and_saveexec_b64 s[2:3], s[6:7]
	s_cbranch_execz .LBB0_170
.LBB0_170:
	s_or_b64 exec, exec, s[2:3]
	v_mov_b32_e32 v0, s25
	v_add_co_u32_e32 v2, vcc, 0x2000, v0
	v_mov_b32_e32 v0, s24
	s_nop 0
	v_addc_co_u32_e32 v3, vcc, 0, v0, vcc
	s_waitcnt vmcnt(0) lgkmcnt(0)
	buffer_inv sc1
	global_atomic_add v[2:3], v218, off offset:1024
	s_waitcnt vmcnt(0)
